# pp_v29 (unit-prefetch temp moved to v[248:251]) + IDX selection: next query's score row (sc1 loads) prefetched at the head of the current query
# speedup vs baseline: 1.0152x; 1.0000x over previous
.Lix_have:
	v_mov_b64_e32 v[66:67], v[248:249]
	v_mov_b64_e32 v[68:69], v[250:251]

.LBB0_579:
	s_cmp_eq_u32 s58, 3
	s_cbranch_scc1 .Lix_nopf
	s_cmp_eq_u32 s58, 0
	s_cselect_b32 s64, s36, s37
	s_cmp_eq_u32 s58, 2
	s_cselect_b32 s64, s38, s64
	s_lshl_b32 s65, s64, 5
	s_add_u32 s66, s34, s65
	s_addc_u32 s67, s35, 0
	v_mov_b32_e32 v151, s67
	v_or_b32_e32 v150, s66, v114
	v_lshlrev_b64 v[150:151], 10, v[150:151]
	v_lshl_add_u64 v[150:151], v[116:117], 0, v[150:151]
	global_load_dwordx4 v[248:251], v[150:151], off
	global_load_dwordx4 v[70:73], v[150:151], off offset:32
	global_load_dwordx4 v[74:77], v[150:151], off offset:64
	global_load_dwordx4 v[78:81], v[150:151], off offset:96
	v_mov_b32_e32 v153, s67
	v_or_b32_e32 v152, s66, v118
	v_lshlrev_b64 v[152:153], 5, v[152:153]
	v_lshl_add_u64 v[154:155], s[18:19], 0, v[152:153]
	global_load_dwordx4 v[82:85], v[154:155], off offset:16
	global_load_dwordx4 v[86:89], v[154:155], off
	v_or_b32_e32 v152, 32, v152
	v_lshl_add_u64 v[152:153], s[18:19], 0, v[152:153]
	global_load_dwordx4 v[98:101], v[120:121], off
	global_load_dwordx4 v[102:105], v[122:123], off
	global_load_dwordx4 v[106:109], v[124:125], off
	global_load_dwordx4 v[110:113], v[126:127], off
	global_load_dwordx4 v[90:93], v[152:153], off offset:16
	global_load_dwordx4 v[94:97], v[152:153], off
.Lix_nopf:
	s_waitcnt vmcnt(0)
	s_cmp_lt_u32 s33, 64
	s_mov_b64 s[14:15], -1
	s_cbranch_scc1 .LBB0_698
	s_lshr_b32 s14, s33, 1
	s_add_i32 s2, s42, s31
	v_cmp_ge_u32_e64 s[14:15], s14, v176
	s_mov_b32 s43, 0
	v_cmp_ge_u32_e32 vcc, s2, v136
	s_and_saveexec_b64 s[64:65], vcc
	s_cbranch_execz .Lsel2_p0
	s_mov_b32 s66, s31
	s_mov_b32 s67, s21
	s_lshl_b64 s[66:67], s[66:67], 13
	v_lshl_add_u64 v[226:227], v[138:139], 0, s[66:67]
	global_load_dwordx4 v[194:197], v[226:227], off sc1
	global_load_dwordx4 v[198:201], v[226:227], off offset:16 sc1
	global_load_dwordx4 v[202:205], v[226:227], off offset:32 sc1
	global_load_dwordx4 v[206:209], v[226:227], off offset:48 sc1
	global_load_dwordx4 v[210:213], v[226:227], off offset:64 sc1
	global_load_dwordx4 v[214:217], v[226:227], off offset:80 sc1
	global_load_dwordx4 v[218:221], v[226:227], off offset:112 sc1
	global_load_dwordx4 v[222:225], v[226:227], off offset:96 sc1
.Lsel2_p0:
	s_or_b64 exec, exec, s[64:65]
	s_branch .LBB0_582

.LBB0_582:
	s_add_i32 s20, s2, s43
	v_cmp_ge_u32_e32 vcc, s20, v136
	v_mov_b32_e32 v1, 0
	v_mov_b32_e32 v3, 0
	v_mov_b32_e32 v4, 0
	v_mov_b32_e32 v5, 0
	v_mov_b32_e32 v6, 0
	v_mov_b32_e32 v7, 0
	v_mov_b32_e32 v8, 0
	v_mov_b32_e32 v9, 0
	v_mov_b32_e32 v11, 0
	v_mov_b32_e32 v19, 0
	v_mov_b32_e32 v20, 0
	v_mov_b32_e32 v21, 0
	v_mov_b32_e32 v22, 0
	v_mov_b32_e32 v23, 0
	v_mov_b32_e32 v24, 0
	v_mov_b32_e32 v25, 0
	v_mov_b32_e32 v2, 0
	v_mov_b32_e32 v12, 0
	v_mov_b32_e32 v13, 0
	v_mov_b32_e32 v14, 0
	v_mov_b32_e32 v15, 0
	v_mov_b32_e32 v16, 0
	v_mov_b32_e32 v17, 0
	v_mov_b32_e32 v18, 0
	v_mov_b32_e32 v26, 0
	v_mov_b32_e32 v27, 0
	v_mov_b32_e32 v29, 0
	v_mov_b32_e32 v30, 0
	v_mov_b32_e32 v31, 0
	v_mov_b32_e32 v32, 0
	v_mov_b32_e32 v33, 0
	v_mov_b32_e32 v34, 0
	v_mov_b32_e32 v35, 0
	s_and_saveexec_b64 s[16:17], vcc
	s_cbranch_execz .LBB0_584
	s_cmp_lg_u32 s43, 0
	s_cbranch_scc1 .Lsel2_w1
	s_waitcnt vmcnt(0)
.Lsel2_w1:
	s_waitcnt vmcnt(1)
	v_mov_b64_e32 v[4:5], v[194:195]
	v_mov_b64_e32 v[6:7], v[196:197]
	v_mov_b64_e32 v[8:9], v[198:199]
	v_mov_b64_e32 v[10:11], v[200:201]
	v_mov_b64_e32 v[12:13], v[202:203]
	v_mov_b64_e32 v[14:15], v[204:205]
	v_mov_b64_e32 v[24:25], v[206:207]
	v_mov_b64_e32 v[26:27], v[208:209]
	v_mov_b64_e32 v[28:29], v[210:211]
	v_mov_b64_e32 v[30:31], v[212:213]
	v_mov_b64_e32 v[32:33], v[214:215]
	v_mov_b64_e32 v[34:35], v[216:217]
	v_mov_b64_e32 v[36:37], v[218:219]
	v_mov_b64_e32 v[38:39], v[220:221]
	v_mov_b64_e32 v[40:41], v[222:223]
	v_mov_b64_e32 v[42:43], v[224:225]
	s_cmp_eq_u32 s43, 3
	s_cbranch_scc1 .Lsel2_np
	s_mov_b64 s[64:65], exec
	s_mov_b64 exec, s[16:17]
	s_add_i32 s66, s20, 1
	v_cmp_ge_u32_e32 vcc, s66, v136
	s_and_b64 exec, exec, vcc
	s_cbranch_execz .Lsel2_pe
	s_add_i32 s66, s43, 1
	s_or_b32 s66, s66, s31
	s_mov_b32 s67, s21
	s_lshl_b64 s[66:67], s[66:67], 13
	v_lshl_add_u64 v[226:227], v[138:139], 0, s[66:67]
	global_load_dwordx4 v[194:197], v[226:227], off sc1
	global_load_dwordx4 v[198:201], v[226:227], off offset:16 sc1
	global_load_dwordx4 v[202:205], v[226:227], off offset:32 sc1
	global_load_dwordx4 v[206:209], v[226:227], off offset:48 sc1
	global_load_dwordx4 v[210:213], v[226:227], off offset:64 sc1
	global_load_dwordx4 v[214:217], v[226:227], off offset:80 sc1
	global_load_dwordx4 v[218:221], v[226:227], off offset:112 sc1
	global_load_dwordx4 v[222:225], v[226:227], off offset:96 sc1
.Lsel2_pe:
	s_mov_b64 exec, s[64:65]
.Lsel2_np:
	v_lshrrev_b32_e32 v2, 15, v4
	v_lshrrev_b32_e32 v3, 15, v5
	v_lshrrev_b32_e32 v16, 15, v6
	v_lshrrev_b32_e32 v17, 15, v7
	v_lshrrev_b32_e32 v18, 15, v8
	v_lshrrev_b32_e32 v19, 15, v9
	v_lshrrev_b32_e32 v20, 15, v10
	v_and_b32_e32 v2, 0x10001, v2
	v_and_b32_e32 v3, 0x10001, v3
	v_and_b32_e32 v16, 0x10001, v16
	v_and_b32_e32 v17, 0x10001, v17
	v_and_b32_e32 v18, 0x10001, v18
	v_and_b32_e32 v19, 0x10001, v19
	v_and_b32_e32 v20, 0x10001, v20
	v_mul_u32_u24_e32 v2, 0x7fff, v2
	v_mul_u32_u24_e32 v53, 0x7fff, v3
	v_mul_u32_u24_e32 v16, 0x7fff, v16
	v_mul_u32_u24_e32 v17, 0x7fff, v17
	v_mul_u32_u24_e32 v18, 0x7fff, v18
	v_mul_u32_u24_e32 v19, 0x7fff, v19
	v_mul_u32_u24_e32 v20, 0x7fff, v20
	v_lshrrev_b32_e32 v22, 15, v12
	v_lshrrev_b32_e32 v45, 15, v15
	v_bitop3_b32 v3, v2, v4, s41 bitop3:0x36
	v_bitop3_b32 v4, v53, v5, s41 bitop3:0x36
	v_bitop3_b32 v5, v16, v6, s41 bitop3:0x36
	v_bitop3_b32 v6, v17, v7, s41 bitop3:0x36
	v_bitop3_b32 v7, v18, v8, s41 bitop3:0x36
	v_bitop3_b32 v8, v19, v9, s41 bitop3:0x36
	v_bitop3_b32 v9, v20, v10, s41 bitop3:0x36
	v_lshrrev_b32_e32 v10, 15, v31
	v_and_b32_e32 v22, 0x10001, v22
	v_and_b32_e32 v45, 0x10001, v45
	v_and_b32_e32 v10, 0x10001, v10
	v_mul_u32_u24_e32 v22, 0x7fff, v22
	v_mul_u32_u24_e32 v45, 0x7fff, v45
	v_mul_u32_u24_e32 v10, 0x7fff, v10
	v_bitop3_b32 v19, v22, v12, s41 bitop3:0x36
	v_bitop3_b32 v22, v45, v15, s41 bitop3:0x36
	v_bitop3_b32 v15, v10, v31, s41 bitop3:0x36
	v_lshrrev_b32_e32 v10, 15, v32
	v_and_b32_e32 v10, 0x10001, v10
	v_mul_u32_u24_e32 v10, 0x7fff, v10
	v_bitop3_b32 v16, v10, v32, s41 bitop3:0x36
	v_lshrrev_b32_e32 v10, 15, v33
	v_and_b32_e32 v10, 0x10001, v10
	v_mul_u32_u24_e32 v10, 0x7fff, v10
	v_bitop3_b32 v17, v10, v33, s41 bitop3:0x36
	v_lshrrev_b32_e32 v10, 15, v34
	v_and_b32_e32 v10, 0x10001, v10
	v_mul_u32_u24_e32 v10, 0x7fff, v10
	v_lshrrev_b32_e32 v23, 15, v13
	v_lshrrev_b32_e32 v46, 15, v24
	v_lshrrev_b32_e32 v47, 15, v25
	v_lshrrev_b32_e32 v48, 15, v26
	v_bitop3_b32 v18, v10, v34, s41 bitop3:0x36
	v_lshrrev_b32_e32 v10, 15, v35
	v_and_b32_e32 v23, 0x10001, v23
	v_and_b32_e32 v46, 0x10001, v46
	v_and_b32_e32 v47, 0x10001, v47
	v_and_b32_e32 v48, 0x10001, v48
	v_and_b32_e32 v10, 0x10001, v10
	v_mul_u32_u24_e32 v23, 0x7fff, v23
	v_mul_u32_u24_e32 v46, 0x7fff, v46
	v_mul_u32_u24_e32 v47, 0x7fff, v47
	v_mul_u32_u24_e32 v48, 0x7fff, v48
	v_mul_u32_u24_e32 v10, 0x7fff, v10
	v_lshrrev_b32_e32 v49, 15, v27
	v_bitop3_b32 v20, v23, v13, s41 bitop3:0x36
	v_bitop3_b32 v23, v46, v24, s41 bitop3:0x36
	v_bitop3_b32 v24, v47, v25, s41 bitop3:0x36
	v_bitop3_b32 v25, v48, v26, s41 bitop3:0x36
	v_bitop3_b32 v26, v10, v35, s41 bitop3:0x36
	v_lshrrev_b32_e32 v10, 15, v40
	v_and_b32_e32 v49, 0x10001, v49
	v_and_b32_e32 v10, 0x10001, v10
	v_mul_u32_u24_e32 v49, 0x7fff, v49
	v_mul_u32_u24_e32 v10, 0x7fff, v10
	v_lshrrev_b32_e32 v51, 15, v29
	v_bitop3_b32 v2, v49, v27, s41 bitop3:0x36
	v_bitop3_b32 v27, v10, v40, s41 bitop3:0x36
	v_lshrrev_b32_e32 v10, 15, v41
	v_and_b32_e32 v51, 0x10001, v51
	v_and_b32_e32 v10, 0x10001, v10
	v_mul_u32_u24_e32 v51, 0x7fff, v51
	v_mul_u32_u24_e32 v10, 0x7fff, v10
	v_lshrrev_b32_e32 v21, 15, v11
	v_lshrrev_b32_e32 v44, 15, v14
	v_lshrrev_b32_e32 v52, 15, v30
	v_bitop3_b32 v13, v51, v29, s41 bitop3:0x36
	v_bitop3_b32 v29, v10, v41, s41 bitop3:0x36
	v_lshrrev_b32_e32 v10, 15, v42
	v_and_b32_e32 v21, 0x10001, v21
	v_and_b32_e32 v44, 0x10001, v44
	v_and_b32_e32 v52, 0x10001, v52
	v_and_b32_e32 v10, 0x10001, v10
	v_mul_u32_u24_e32 v21, 0x7fff, v21
	v_mul_u32_u24_e32 v44, 0x7fff, v44
	v_mul_u32_u24_e32 v52, 0x7fff, v52
	v_mul_u32_u24_e32 v10, 0x7fff, v10
	v_bitop3_b32 v11, v21, v11, s41 bitop3:0x36
	v_bitop3_b32 v21, v44, v14, s41 bitop3:0x36
	v_bitop3_b32 v14, v52, v30, s41 bitop3:0x36
	v_bitop3_b32 v30, v10, v42, s41 bitop3:0x36
	v_lshrrev_b32_e32 v10, 15, v43
	v_and_b32_e32 v10, 0x10001, v10
	v_mul_u32_u24_e32 v10, 0x7fff, v10
	v_bitop3_b32 v31, v10, v43, s41 bitop3:0x36
	v_lshrrev_b32_e32 v10, 15, v36
	v_and_b32_e32 v10, 0x10001, v10
	v_mul_u32_u24_e32 v10, 0x7fff, v10
	v_bitop3_b32 v32, v10, v36, s41 bitop3:0x36
	v_lshrrev_b32_e32 v10, 15, v37
	v_and_b32_e32 v10, 0x10001, v10
	v_mul_u32_u24_e32 v10, 0x7fff, v10
	v_bitop3_b32 v33, v10, v37, s41 bitop3:0x36
	v_lshrrev_b32_e32 v10, 15, v38
	v_and_b32_e32 v10, 0x10001, v10
	v_mul_u32_u24_e32 v10, 0x7fff, v10
	v_lshrrev_b32_e32 v50, 15, v28
	v_bitop3_b32 v34, v10, v38, s41 bitop3:0x36
	v_lshrrev_b32_e32 v10, 15, v39
	v_and_b32_e32 v50, 0x10001, v50
	v_and_b32_e32 v10, 0x10001, v10
	v_mul_u32_u24_e32 v50, 0x7fff, v50
	v_mul_u32_u24_e32 v10, 0x7fff, v10
	v_bitop3_b32 v12, v50, v28, s41 bitop3:0x36
	v_bitop3_b32 v35, v10, v39, s41 bitop3:0x36

.LBB0_698:
	s_and_b64 vcc, exec, s[14:15]
	s_cbranch_vccz .LBB0_566
	s_and_b32 s14, s33, 62
	s_add_i32 s14, s14, 2
	s_add_i32 s2, s42, s31
	v_cmp_gt_u32_e64 s[14:15], s14, v176
	s_mov_b32 s33, 0
	v_cmp_ge_u32_e32 vcc, s2, v162
	s_and_saveexec_b64 s[64:65], vcc
	s_cbranch_execz .Lsel1_p0
	s_mov_b32 s66, s31
	s_mov_b32 s67, s21
	s_lshl_b64 s[66:67], s[66:67], 13
	v_lshl_add_u64 v[226:227], v[142:143], 0, s[66:67]
	global_load_dwordx4 v[194:197], v[226:227], off sc1
	global_load_dwordx4 v[198:201], v[226:227], off offset:16 sc1
	global_load_dwordx4 v[202:205], v[226:227], off offset:32 sc1
	global_load_dwordx4 v[206:209], v[226:227], off offset:48 sc1

.LBB0_701:
	s_add_i32 s20, s2, s33
	v_cmp_ge_u32_e32 vcc, s20, v162
	v_mov_b32_e32 v1, 0
	v_mov_b32_e32 v2, 0
	v_mov_b32_e32 v3, 0
	v_mov_b32_e32 v4, 0
	v_mov_b32_e32 v5, 0
	v_mov_b32_e32 v6, 0
	v_mov_b32_e32 v7, 0
	v_mov_b32_e32 v8, 0
	v_mov_b32_e32 v9, 0
	v_mov_b32_e32 v10, 0
	v_mov_b32_e32 v11, 0
	v_mov_b32_e32 v12, 0
	v_mov_b32_e32 v13, 0
	v_mov_b32_e32 v14, 0
	v_mov_b32_e32 v15, 0
	v_mov_b32_e32 v16, 0
	v_mov_b32_e32 v17, 0
	s_and_saveexec_b64 s[16:17], vcc
	s_cbranch_execz .LBB0_703
	s_cmp_lg_u32 s33, 0
	s_cbranch_scc1 .Lsel1_w1
	s_waitcnt vmcnt(0)
.Lsel1_w1:
	s_waitcnt vmcnt(1)
	v_mov_b64_e32 v[2:3], v[194:195]
	v_mov_b64_e32 v[4:5], v[196:197]
	v_mov_b64_e32 v[6:7], v[198:199]
	v_mov_b64_e32 v[8:9], v[200:201]
	v_mov_b64_e32 v[10:11], v[202:203]
	v_mov_b64_e32 v[12:13], v[204:205]
	v_mov_b64_e32 v[14:15], v[206:207]
	v_mov_b64_e32 v[16:17], v[208:209]
	s_cmp_eq_u32 s33, 3
	s_cbranch_scc1 .Lsel1_np
	s_mov_b64 s[64:65], exec
	s_mov_b64 exec, s[16:17]
	s_add_i32 s66, s20, 1
	v_cmp_ge_u32_e32 vcc, s66, v162
	s_and_b64 exec, exec, vcc
	s_cbranch_execz .Lsel1_pe
	s_add_i32 s66, s33, 1
	s_or_b32 s66, s66, s31
	s_mov_b32 s67, s21
	s_lshl_b64 s[66:67], s[66:67], 13
	v_lshl_add_u64 v[226:227], v[142:143], 0, s[66:67]
	global_load_dwordx4 v[194:197], v[226:227], off sc1
	global_load_dwordx4 v[198:201], v[226:227], off offset:16 sc1
	global_load_dwordx4 v[202:205], v[226:227], off offset:32 sc1
	global_load_dwordx4 v[206:209], v[226:227], off offset:48 sc1

.Lsel1_np:
	v_lshrrev_b32_e32 v18, 15, v2
	v_lshrrev_b32_e32 v19, 15, v3
	v_lshrrev_b32_e32 v20, 15, v4
	v_lshrrev_b32_e32 v21, 15, v5
	v_lshrrev_b32_e32 v22, 15, v6
	v_lshrrev_b32_e32 v23, 15, v7
	v_lshrrev_b32_e32 v24, 15, v8
	v_lshrrev_b32_e32 v25, 15, v9
	v_lshrrev_b32_e32 v26, 15, v10
	v_lshrrev_b32_e32 v27, 15, v11
	v_lshrrev_b32_e32 v28, 15, v12
	v_lshrrev_b32_e32 v29, 15, v13
	v_lshrrev_b32_e32 v30, 15, v14
	v_lshrrev_b32_e32 v31, 15, v15
	v_lshrrev_b32_e32 v32, 15, v16
	v_lshrrev_b32_e32 v33, 15, v17
	v_and_b32_e32 v18, 0x10001, v18
	v_and_b32_e32 v19, 0x10001, v19
	v_and_b32_e32 v20, 0x10001, v20
	v_and_b32_e32 v21, 0x10001, v21
	v_and_b32_e32 v22, 0x10001, v22
	v_and_b32_e32 v23, 0x10001, v23
	v_and_b32_e32 v24, 0x10001, v24
	v_and_b32_e32 v25, 0x10001, v25
	v_and_b32_e32 v26, 0x10001, v26
	v_and_b32_e32 v27, 0x10001, v27
	v_and_b32_e32 v28, 0x10001, v28
	v_and_b32_e32 v29, 0x10001, v29
	v_and_b32_e32 v30, 0x10001, v30
	v_and_b32_e32 v31, 0x10001, v31
	v_and_b32_e32 v32, 0x10001, v32
	v_and_b32_e32 v33, 0x10001, v33
	v_mul_u32_u24_e32 v18, 0x7fff, v18
	v_mul_u32_u24_e32 v19, 0x7fff, v19
	v_mul_u32_u24_e32 v20, 0x7fff, v20
	v_mul_u32_u24_e32 v21, 0x7fff, v21
	v_mul_u32_u24_e32 v22, 0x7fff, v22
	v_mul_u32_u24_e32 v23, 0x7fff, v23
	v_mul_u32_u24_e32 v24, 0x7fff, v24
	v_mul_u32_u24_e32 v25, 0x7fff, v25
	v_mul_u32_u24_e32 v26, 0x7fff, v26
	v_mul_u32_u24_e32 v27, 0x7fff, v27
	v_mul_u32_u24_e32 v28, 0x7fff, v28
	v_mul_u32_u24_e32 v29, 0x7fff, v29
	v_mul_u32_u24_e32 v30, 0x7fff, v30
	v_mul_u32_u24_e32 v31, 0x7fff, v31
	v_mul_u32_u24_e32 v32, 0x7fff, v32
	v_mul_u32_u24_e32 v33, 0x7fff, v33
	v_bitop3_b32 v2, v18, v2, s41 bitop3:0x36
	v_bitop3_b32 v3, v19, v3, s41 bitop3:0x36
	v_bitop3_b32 v4, v20, v4, s41 bitop3:0x36
	v_bitop3_b32 v5, v21, v5, s41 bitop3:0x36
	v_bitop3_b32 v6, v22, v6, s41 bitop3:0x36
	v_bitop3_b32 v7, v23, v7, s41 bitop3:0x36
	v_bitop3_b32 v8, v24, v8, s41 bitop3:0x36
	v_bitop3_b32 v9, v25, v9, s41 bitop3:0x36
	v_bitop3_b32 v10, v26, v10, s41 bitop3:0x36
	v_bitop3_b32 v11, v27, v11, s41 bitop3:0x36
	v_bitop3_b32 v12, v28, v12, s41 bitop3:0x36
	v_bitop3_b32 v13, v29, v13, s41 bitop3:0x36
	v_bitop3_b32 v14, v30, v14, s41 bitop3:0x36
	v_bitop3_b32 v15, v31, v15, s41 bitop3:0x36
	v_bitop3_b32 v16, v32, v16, s41 bitop3:0x36
	v_bitop3_b32 v17, v33, v17, s41 bitop3:0x36
